# D1+A2+B1 + QK prefetch (A1) + softmax static prio 3
# baseline (speedup 1.0000x reference)
; #define A2_WRITET(buf) do { char* kd_ = lds + L_K + (buf) * SHM_K; char* vd_ = lds + L_V + (buf) * 2 * SHM_V; \
;         *(bf16x8*)(kd_ + kws) = sk0; *(bf16x8*)(kd_ + kws + 32 * 256) = sk1; *(bf16x8*)(vd_ + vst0) = sv00; *(bf16x8*)(vd_ + vst1) = sv01; *(bf16x8*)(vd_ + SHM_V + vst0) = sv10; *(bf16x8*)(vd_ + SHM_V + vst1) = sv11; } while (0)
; __device__ __forceinline__ void attn2_block(const Blk& c, char* lds) {
;     ...
;     if (wid < 4) {
;         bf16x8 qr[8];
; #pragma unroll
;         for (int d0 = 0; d0 < 8; ++d0) qr[d0] = att::load8(c.Q + (size_t)(g * 32 + r32) * D + d0 * 16 + hi * 8);
;         asm volatile("s_waitcnt vmcnt(0)" ::: "memory"); A2_WRITET(0); __syncthreads();
;         const int qlo = c.P0 + g * 32, qm = qlo + r32 - 4 * hi;
;         const float* bt = (const float*)(lds + L_BT) + c.hm * 256;
;         float m_reg = -1e30f, l_reg = 0.f;
;         for (int s = 0; s <= NT; ++s) {
.LBB0_551:
	s_setprio 3
	s_or_b64 s[2:3], s[14:15], s[30:31]
	s_lshl_b32 s10, s82, 5
	s_lshl_b64 s[2:3], s[2:3], 8
	s_add_u32 s2, s27, s2
	v_or_b32_e32 v2, s10, v211
	s_addc_u32 s3, s34, s3
	v_lshlrev_b32_e32 v2, 8, v2
	v_lshl_add_u64 v[4:5], s[2:3], 0, v[2:3]
	v_mov_b32_e32 v217, v3
	v_lshl_add_u64 v[4:5], v[4:5], 0, v[216:217]
	global_load_dwordx4 v[104:107], v[4:5], off
	global_load_dwordx4 v[100:103], v[4:5], off offset:32
	global_load_dwordx4 v[96:99], v[4:5], off offset:64
	global_load_dwordx4 v[92:95], v[4:5], off offset:96
	global_load_dwordx4 v[88:91], v[4:5], off offset:128
	global_load_dwordx4 v[84:87], v[4:5], off offset:160
	global_load_dwordx4 v[80:83], v[4:5], off offset:192
	global_load_dwordx4 v[76:79], v[4:5], off offset:224
	s_or_b32 s85, s10, s30
	s_add_i32 s10, s30, s10
	s_waitcnt vmcnt(0)
	v_lshlrev_b32_e32 v4, 4, v211
	s_movk_i32 s2, 0x70
	s_lshl_b32 s11, s30, 8
	s_sub_i32 s10, s10, 27
	v_and_b32_e32 v5, 0x70, v4
	v_bitop3_b32 v121, v216, v4, s2 bitop3:0x78
	s_movk_i32 s2, 0x60
	v_lshlrev_b32_e32 v114, 2, v226
	s_and_b32 s11, s11, 0x1fc000
	v_add_u32_e32 v4, s10, v211
	v_mov_b32_e32 v215, v213
	v_add_u32_e32 v116, 0x10000, v229
	v_lshl_add_u32 v2, v211, 2, s17
	v_lshlrev_b32_e32 v119, 8, v211
	v_bitop3_b32 v122, v216, v5, 32 bitop3:0x36
	v_bitop3_b32 v123, v216, v5, 64 bitop3:0x36
	v_bitop3_b32 v124, v216, v5, s2 bitop3:0x36
	s_add_i32 s86, s85, 0xffffff80
	v_lshl_add_u32 v112, v225, 4, s16
	v_cmp_gt_u32_e64 s[2:3], 32, v225
	s_mov_b32 s84, 0
	v_cmp_eq_u32_e64 s[4:5], 0, v225
	s_add_u32 s87, s11, 0x4000
	v_sub_u32_e32 v125, v4, v114
	v_lshl_add_u64 v[108:109], s[46:47], 0, v[214:215]
	v_lshl_add_u64 v[110:111], s[58:59], 0, v[214:215]
	v_mov_b32_e32 v117, 0
	v_mov_b32_e32 v113, 0xf149f2ca
	s_mov_b64 s[82:83], 0
	s_mov_b32 s30, 0
	s_waitcnt lgkmcnt(0)
	s_barrier
